# v9 + background weight-conversion stores (conv_queue, 32 sites) made nontemporal so the bf16 weight copies stream past the caches the concurrent in-proj GEMM works from
# speedup vs baseline: 1.0130x; 1.0130x over previous
.LBB0_503:
	s_or_b64 exec, exec, s[10:11]
	ds_write2_b32 v176, v32, v33 offset1:1
	ds_write2_b32 v176, v34, v35 offset0:2 offset1:3
	ds_write2_b32 v178, v36, v37 offset1:1
	ds_write2_b32 v179, v38, v39 offset1:1
	ds_write2_b32 v180, v44, v45 offset1:1
	ds_write2_b32 v181, v46, v47 offset1:1
	ds_write2_b32 v182, v48, v49 offset1:1
	ds_write2_b32 v183, v50, v51 offset1:1
	ds_write2_b32 v184, v56, v57 offset1:1
	ds_write2_b32 v185, v58, v59 offset1:1
	ds_write2_b32 v186, v60, v61 offset1:1
	ds_write2_b32 v187, v62, v63 offset1:1
	ds_write2_b32 v188, v68, v69 offset1:1
	ds_write2_b32 v189, v70, v71 offset1:1
	ds_write2_b32 v190, v72, v73 offset1:1
	ds_write2_b32 v191, v74, v75 offset1:1
	ds_write2_b32 v192, v80, v81 offset1:1
	ds_write2_b32 v193, v82, v83 offset1:1
	ds_write2_b32 v194, v84, v85 offset1:1
	ds_write2_b32 v195, v86, v87 offset1:1
	ds_write2_b32 v196, v92, v93 offset1:1
	ds_write2_b32 v197, v94, v95 offset1:1
	ds_write2_b32 v198, v96, v97 offset1:1
	ds_write2_b32 v199, v98, v99 offset1:1
	ds_write2_b32 v200, v104, v105 offset1:1
	ds_write2_b32 v201, v106, v107 offset1:1
	ds_write2_b32 v202, v108, v109 offset1:1
	ds_write2_b32 v203, v110, v111 offset1:1
	ds_write2_b32 v204, v116, v117 offset1:1
	ds_write2_b32 v205, v118, v119 offset1:1
	ds_write2_b32 v206, v120, v121 offset1:1
	ds_write2_b32 v207, v122, v123 offset1:1
	s_waitcnt lgkmcnt(0)
	ds_read2_b32 v[182:183], v171 offset0:65 offset1:73
	ds_read2_b32 v[184:185], v171 offset1:8
	ds_read2_b32 v[186:187], v171 offset0:130 offset1:138
	ds_read2_b32 v[188:189], v171 offset0:195 offset1:203
	ds_read2_b32 v[190:191], v177 offset0:4 offset1:12
	ds_read2_b32 v[192:193], v177 offset0:69 offset1:77
	ds_read2_b32 v[194:195], v177 offset0:134 offset1:142
	ds_read2_b32 v[196:197], v177 offset0:199 offset1:207
	v_lshl_add_u64 v[198:199], v[150:151], 0, v[128:129]
	s_waitcnt lgkmcnt(6)
	v_cvt_pk_bf16_f32 v178, v184, v182
	s_waitcnt lgkmcnt(4)
	v_cvt_pk_bf16_f32 v179, v186, v188
	s_waitcnt lgkmcnt(2)
	v_cvt_pk_bf16_f32 v180, v190, v192
	s_waitcnt lgkmcnt(0)
	v_cvt_pk_bf16_f32 v181, v194, v196
	v_lshl_add_u64 v[200:201], v[198:199], 0, v[134:135]
	global_store_dwordx4 v[200:201], v[178:181], off nt
	v_add_u32_e32 v172, 16, v172
	v_add_u32_e32 v173, 0x10000, v173
	v_cvt_pk_bf16_f32 v178, v185, v183
	v_cvt_pk_bf16_f32 v179, v187, v189
	v_cvt_pk_bf16_f32 v180, v191, v193
	v_cvt_pk_bf16_f32 v181, v195, v197
	ds_read2_b32 v[184:185], v171 offset0:81 offset1:89
	ds_read2_b32 v[186:187], v171 offset0:16 offset1:24
	ds_read2_b32 v[188:189], v171 offset0:146 offset1:154
	ds_read2_b32 v[190:191], v171 offset0:211 offset1:219
	ds_read2_b32 v[192:193], v177 offset0:20 offset1:28
	ds_read2_b32 v[194:195], v177 offset0:85 offset1:93
	ds_read2_b32 v[196:197], v177 offset0:150 offset1:158
	ds_read2_b32 v[200:201], v177 offset0:215 offset1:223
	v_lshl_add_u64 v[182:183], v[198:199], 0, v[136:137]
	global_store_dwordx4 v[182:183], v[178:181], off nt
	v_lshl_add_u64 v[182:183], v[198:199], 0, v[138:139]
	v_add_u32_e32 v174, 0x100, v174
	s_waitcnt lgkmcnt(6)
	v_cvt_pk_bf16_f32 v178, v186, v184
	s_waitcnt lgkmcnt(4)
	v_cvt_pk_bf16_f32 v179, v188, v190
	s_waitcnt lgkmcnt(2)
	v_cvt_pk_bf16_f32 v180, v192, v194
	s_waitcnt lgkmcnt(0)
	v_cvt_pk_bf16_f32 v181, v196, v200
	global_store_dwordx4 v[182:183], v[178:181], off nt
	v_lshl_add_u64 v[182:183], v[198:199], 0, v[140:141]
	v_add_u32_e32 v175, 0x400, v175
	v_cvt_pk_bf16_f32 v178, v187, v185
	v_cvt_pk_bf16_f32 v179, v189, v191
	v_cvt_pk_bf16_f32 v180, v193, v195
	v_cvt_pk_bf16_f32 v181, v197, v201
	ds_read2_b32 v[184:185], v171 offset0:32 offset1:40
	ds_read2_b32 v[186:187], v171 offset0:97 offset1:105
	ds_read2_b32 v[188:189], v171 offset0:162 offset1:170
	ds_read2_b32 v[190:191], v171 offset0:227 offset1:235
	ds_read2_b32 v[192:193], v177 offset0:36 offset1:44
	ds_read2_b32 v[194:195], v177 offset0:101 offset1:109
	ds_read2_b32 v[196:197], v177 offset0:166 offset1:174
	ds_read2_b32 v[200:201], v177 offset0:231 offset1:239
	global_store_dwordx4 v[182:183], v[178:181], off nt
	v_lshl_add_u64 v[182:183], v[198:199], 0, v[142:143]
	s_orn2_b64 s[4:5], vcc, exec
	s_waitcnt lgkmcnt(6)
	v_cvt_pk_bf16_f32 v178, v184, v186
	s_waitcnt lgkmcnt(4)
	v_cvt_pk_bf16_f32 v179, v188, v190
	s_waitcnt lgkmcnt(2)
	v_cvt_pk_bf16_f32 v180, v192, v194
	s_waitcnt lgkmcnt(0)
	v_cvt_pk_bf16_f32 v181, v196, v200
	global_store_dwordx4 v[182:183], v[178:181], off nt
	v_lshl_add_u64 v[182:183], v[198:199], 0, v[144:145]
	s_nop 0
	v_cvt_pk_bf16_f32 v178, v185, v187
	v_cvt_pk_bf16_f32 v179, v189, v191
	v_cvt_pk_bf16_f32 v180, v193, v195
	v_cvt_pk_bf16_f32 v181, v197, v201
	ds_read2_b32 v[184:185], v171 offset0:48 offset1:56
	ds_read2_b32 v[186:187], v171 offset0:113 offset1:121
	ds_read2_b32 v[188:189], v171 offset0:178 offset1:186
	ds_read2_b32 v[190:191], v171 offset0:243 offset1:251
	ds_read2_b32 v[192:193], v177 offset0:52 offset1:60
	ds_read2_b32 v[194:195], v177 offset0:117 offset1:125
	ds_read2_b32 v[196:197], v177 offset0:182 offset1:190
	ds_read2_b32 v[200:201], v177 offset0:247 offset1:255
	global_store_dwordx4 v[182:183], v[178:181], off nt
	v_lshl_add_u64 v[182:183], v[198:199], 0, v[146:147]
	s_waitcnt lgkmcnt(6)
	v_cvt_pk_bf16_f32 v178, v184, v186
	s_waitcnt lgkmcnt(4)
	v_cvt_pk_bf16_f32 v179, v188, v190
	s_waitcnt lgkmcnt(2)
	v_cvt_pk_bf16_f32 v180, v192, v194
	s_waitcnt lgkmcnt(0)
	v_cvt_pk_bf16_f32 v181, v196, v200
	global_store_dwordx4 v[182:183], v[178:181], off nt
	v_lshl_add_u64 v[182:183], v[198:199], 0, v[148:149]
	s_nop 0
	v_cvt_pk_bf16_f32 v178, v185, v187
	v_cvt_pk_bf16_f32 v179, v189, v191
	v_cvt_pk_bf16_f32 v180, v193, v195
	v_cvt_pk_bf16_f32 v181, v197, v201
	global_store_dwordx4 v[182:183], v[178:181], off nt
	s_waitcnt lgkmcnt(0)

.LBB0_519:
	s_or_b64 exec, exec, s[8:9]
	v_add_u32_e32 v178, 0x410, v176
	v_add_u32_e32 v179, 0x418, v176
	v_add_u32_e32 v180, 0x820, v176
	v_add_u32_e32 v181, 0x828, v176
	v_add_u32_e32 v182, 0xc30, v176
	v_add_u32_e32 v183, 0xc38, v176
	v_add_u32_e32 v184, 0x1040, v176
	v_add_u32_e32 v185, 0x1048, v176
	v_add_u32_e32 v186, 0x1450, v176
	v_add_u32_e32 v187, 0x1458, v176
	v_add_u32_e32 v188, 0x1860, v176
	v_add_u32_e32 v189, 0x1868, v176
	v_add_u32_e32 v190, 0x1c70, v176
	v_add_u32_e32 v191, 0x1c78, v176
	v_add_u32_e32 v192, 0x2080, v176
	v_add_u32_e32 v193, 0x2088, v176
	v_add_u32_e32 v194, 0x2490, v176
	v_add_u32_e32 v195, 0x2498, v176
	v_add_u32_e32 v196, 0x28a0, v176
	v_add_u32_e32 v197, 0x28a8, v176
	v_add_u32_e32 v198, 0x2cb0, v176
	v_add_u32_e32 v199, 0x2cb8, v176
	v_add_u32_e32 v200, 0x30c0, v176
	v_add_u32_e32 v201, 0x30c8, v176
	v_add_u32_e32 v202, 0x34d0, v176
	v_add_u32_e32 v203, 0x34d8, v176
	v_add_u32_e32 v204, 0x38e0, v176
	v_add_u32_e32 v205, 0x38e8, v176
	v_add_u32_e32 v206, 0x3cf0, v176
	v_add_u32_e32 v207, 0x3cf8, v176
	s_waitcnt vmcnt(15)
	ds_write2_b32 v176, v0, v1 offset1:1
	ds_write2_b32 v176, v2, v3 offset0:2 offset1:3
	s_waitcnt vmcnt(14)
	ds_write2_b32 v178, v4, v5 offset1:1
	ds_write2_b32 v179, v6, v7 offset1:1
	s_waitcnt vmcnt(13)
	ds_write2_b32 v180, v8, v9 offset1:1
	ds_write2_b32 v181, v10, v11 offset1:1
	s_waitcnt vmcnt(12)
	ds_write2_b32 v182, v12, v13 offset1:1
	ds_write2_b32 v183, v14, v15 offset1:1
	s_waitcnt vmcnt(11)
	ds_write2_b32 v184, v16, v17 offset1:1
	ds_write2_b32 v185, v18, v19 offset1:1
	s_waitcnt vmcnt(10)
	ds_write2_b32 v186, v20, v21 offset1:1
	ds_write2_b32 v187, v22, v23 offset1:1
	s_waitcnt vmcnt(9)
	ds_write2_b32 v188, v24, v25 offset1:1
	ds_write2_b32 v189, v26, v27 offset1:1
	s_waitcnt vmcnt(8)
	ds_write2_b32 v190, v28, v29 offset1:1
	ds_write2_b32 v191, v30, v31 offset1:1
	s_waitcnt vmcnt(7)
	ds_write2_b32 v192, v40, v41 offset1:1
	ds_write2_b32 v193, v42, v43 offset1:1
	s_waitcnt vmcnt(6)
	ds_write2_b32 v194, v52, v53 offset1:1
	ds_write2_b32 v195, v54, v55 offset1:1
	s_waitcnt vmcnt(5)
	ds_write2_b32 v196, v64, v65 offset1:1
	ds_write2_b32 v197, v66, v67 offset1:1
	s_waitcnt vmcnt(4)
	ds_write2_b32 v198, v76, v77 offset1:1
	ds_write2_b32 v199, v78, v79 offset1:1
	s_waitcnt vmcnt(3)
	ds_write2_b32 v200, v88, v89 offset1:1
	ds_write2_b32 v201, v90, v91 offset1:1
	s_waitcnt vmcnt(2)
	ds_write2_b32 v202, v100, v101 offset1:1
	ds_write2_b32 v203, v102, v103 offset1:1
	s_waitcnt vmcnt(1)
	ds_write2_b32 v204, v112, v113 offset1:1
	ds_write2_b32 v205, v114, v115 offset1:1
	s_waitcnt vmcnt(0)
	ds_write2_b32 v206, v124, v125 offset1:1
	ds_write2_b32 v207, v126, v127 offset1:1
	s_waitcnt lgkmcnt(0)
	v_add_u32_e32 v177, 0x400, v171
	ds_read2_b32 v[214:215], v171 offset0:65 offset1:73
	ds_read2_b32 v[216:217], v171 offset1:8
	ds_read2_b32 v[218:219], v171 offset0:130 offset1:138
	ds_read2_b32 v[220:221], v171 offset0:195 offset1:203
	ds_read2_b32 v[222:223], v177 offset0:4 offset1:12
	ds_read2_b32 v[224:225], v177 offset0:69 offset1:77
	ds_read2_b32 v[226:227], v177 offset0:134 offset1:142
	ds_read2_b32 v[228:229], v177 offset0:199 offset1:207
	v_lshlrev_b32_e32 v128, 1, v132
	v_lshl_add_u64 v[212:213], v[152:153], 0, v[128:129]
	s_waitcnt lgkmcnt(6)
	v_cvt_pk_bf16_f32 v208, v216, v214
	s_waitcnt lgkmcnt(4)
	v_cvt_pk_bf16_f32 v209, v218, v220
	s_waitcnt lgkmcnt(2)
	v_cvt_pk_bf16_f32 v210, v222, v224
	s_waitcnt lgkmcnt(0)
	v_cvt_pk_bf16_f32 v211, v226, v228
	v_lshl_add_u64 v[230:231], v[212:213], 0, v[134:135]
	global_store_dwordx4 v[230:231], v[208:211], off nt
	v_lshl_add_u64 v[230:231], v[212:213], 0, v[138:139]
	s_mov_b64 s[4:5], -1
	v_cvt_pk_bf16_f32 v208, v217, v215
	v_cvt_pk_bf16_f32 v209, v219, v221
	v_cvt_pk_bf16_f32 v210, v223, v225
	v_cvt_pk_bf16_f32 v211, v227, v229
	v_lshl_add_u64 v[214:215], v[212:213], 0, v[136:137]
	global_store_dwordx4 v[214:215], v[208:211], off nt
	ds_read2_b32 v[214:215], v171 offset0:81 offset1:89
	ds_read2_b32 v[216:217], v171 offset0:16 offset1:24
	ds_read2_b32 v[218:219], v171 offset0:146 offset1:154
	ds_read2_b32 v[220:221], v171 offset0:211 offset1:219
	ds_read2_b32 v[222:223], v177 offset0:20 offset1:28
	ds_read2_b32 v[224:225], v177 offset0:85 offset1:93
	ds_read2_b32 v[226:227], v177 offset0:150 offset1:158
	ds_read2_b32 v[228:229], v177 offset0:215 offset1:223
	s_waitcnt lgkmcnt(6)
	v_cvt_pk_bf16_f32 v208, v216, v214
	s_waitcnt lgkmcnt(4)
	v_cvt_pk_bf16_f32 v209, v218, v220
	s_waitcnt lgkmcnt(2)
	v_cvt_pk_bf16_f32 v210, v222, v224
	s_waitcnt lgkmcnt(0)
	v_cvt_pk_bf16_f32 v211, v226, v228
	global_store_dwordx4 v[230:231], v[208:211], off nt
	v_lshl_add_u64 v[230:231], v[212:213], 0, v[142:143]
	s_nop 0
	v_cvt_pk_bf16_f32 v208, v217, v215
	v_cvt_pk_bf16_f32 v209, v219, v221
	v_cvt_pk_bf16_f32 v210, v223, v225
	v_cvt_pk_bf16_f32 v211, v227, v229
	v_lshl_add_u64 v[214:215], v[212:213], 0, v[140:141]
	global_store_dwordx4 v[214:215], v[208:211], off nt
	ds_read2_b32 v[214:215], v171 offset0:32 offset1:40
	ds_read2_b32 v[216:217], v171 offset0:97 offset1:105
	ds_read2_b32 v[218:219], v171 offset0:162 offset1:170
	ds_read2_b32 v[220:221], v171 offset0:227 offset1:235
	ds_read2_b32 v[222:223], v177 offset0:36 offset1:44
	ds_read2_b32 v[224:225], v177 offset0:101 offset1:109
	ds_read2_b32 v[226:227], v177 offset0:166 offset1:174
	ds_read2_b32 v[228:229], v177 offset0:231 offset1:239
	s_waitcnt lgkmcnt(6)
	v_cvt_pk_bf16_f32 v208, v214, v216
	s_waitcnt lgkmcnt(4)
	v_cvt_pk_bf16_f32 v209, v218, v220
	s_waitcnt lgkmcnt(2)
	v_cvt_pk_bf16_f32 v210, v222, v224
	s_waitcnt lgkmcnt(0)
	v_cvt_pk_bf16_f32 v211, v226, v228
	global_store_dwordx4 v[230:231], v[208:211], off nt
	v_lshl_add_u64 v[230:231], v[212:213], 0, v[146:147]
	s_nop 0
	v_cvt_pk_bf16_f32 v208, v215, v217
	v_cvt_pk_bf16_f32 v209, v219, v221
	v_cvt_pk_bf16_f32 v210, v223, v225
	v_cvt_pk_bf16_f32 v211, v227, v229
	v_lshl_add_u64 v[214:215], v[212:213], 0, v[144:145]
	global_store_dwordx4 v[214:215], v[208:211], off nt
	ds_read2_b32 v[214:215], v171 offset0:48 offset1:56
	ds_read2_b32 v[216:217], v171 offset0:113 offset1:121
	ds_read2_b32 v[218:219], v171 offset0:178 offset1:186
	ds_read2_b32 v[220:221], v171 offset0:243 offset1:251
	ds_read2_b32 v[222:223], v177 offset0:52 offset1:60
	ds_read2_b32 v[224:225], v177 offset0:117 offset1:125
	ds_read2_b32 v[226:227], v177 offset0:182 offset1:190
	ds_read2_b32 v[228:229], v177 offset0:247 offset1:255
	v_lshl_add_u64 v[212:213], v[212:213], 0, v[148:149]
	s_waitcnt lgkmcnt(6)
	v_cvt_pk_bf16_f32 v208, v214, v216
	s_waitcnt lgkmcnt(4)
	v_cvt_pk_bf16_f32 v209, v218, v220
	s_waitcnt lgkmcnt(2)
	v_cvt_pk_bf16_f32 v210, v222, v224
	s_waitcnt lgkmcnt(0)
	v_cvt_pk_bf16_f32 v211, v226, v228
	global_store_dwordx4 v[230:231], v[208:211], off nt
	s_nop 1
	v_cvt_pk_bf16_f32 v208, v215, v217
	v_cvt_pk_bf16_f32 v209, v219, v221
	v_cvt_pk_bf16_f32 v210, v223, v225
	v_cvt_pk_bf16_f32 v211, v227, v229
	global_store_dwordx4 v[212:213], v[208:211], off nt
	s_waitcnt lgkmcnt(0)
	s_and_saveexec_b64 s[8:9], vcc
	s_cbranch_execz .LBB0_504
	v_add_u32_e32 v154, 16, v154
	v_cmp_ge_i32_e32 vcc, v172, v133
	v_cmp_lt_i32_e64 s[4:5], v172, v133
	s_and_saveexec_b64 s[10:11], s[4:5]
	s_cbranch_execz .LBB0_503
	s_mov_b32 s4, 0x2aaaaaab
	v_mul_hi_i32 v0, v172, s4
	v_lshrrev_b32_e32 v1, 31, v0
	v_ashrrev_i32_e32 v0, 11, v0
	v_add_u32_e32 v4, v0, v1
	v_mul_i32_i24_e32 v8, 0x3000, v4
	v_sub_u32_e32 v11, v172, v8
	s_movk_i32 s4, 0xbff
	v_cmp_lt_i32_e64 s[4:5], s4, v11
	s_and_saveexec_b64 s[14:15], s[4:5]
	s_xor_b64 s[14:15], exec, s[14:15]
	s_cbranch_execz .LBB0_531
	s_movk_i32 s4, 0xfff
	v_lshlrev_b32_e32 v0, 6, v8
	v_cmp_lt_u32_e64 s[4:5], s4, v11
	v_ashrrev_i32_e32 v5, 31, v4
	v_sub_u32_e32 v9, v175, v0
	s_and_saveexec_b64 s[16:17], s[4:5]
	s_xor_b64 s[16:17], exec, s[16:17]
	s_cbranch_execz .LBB0_528
	s_movk_i32 s4, 0x1fff
	v_cmp_lt_u32_e64 s[4:5], s4, v11
	v_lshlrev_b64 v[6:7], 26, v[4:5]
	v_lshlrev_b64 v[4:5], 25, v[4:5]
	s_and_saveexec_b64 s[18:19], s[4:5]
	s_xor_b64 s[4:5], exec, s[18:19]
	s_cbranch_execz .LBB0_525
	v_add_u32_e32 v0, 0xffffe000, v11
	v_lshrrev_b32_e32 v8, 5, v0
	v_readlane_b32 s40, v254, 35
	v_readlane_b32 s48, v254, 43
	v_readlane_b32 s49, v254, 44
	v_lshlrev_b32_e32 v2, 6, v8
	v_mov_b32_e32 v3, v129
	v_lshl_add_u64 v[0:1], s[48:49], 0, v[6:7]
	v_lshlrev_b64 v[2:3], 13, v[2:3]
	v_and_b32_e32 v6, 0x7c0, v9
	v_lshl_add_u64 v[0:1], v[0:1], 0, v[2:3]
	v_lshlrev_b32_e32 v2, 2, v6
	v_mov_b32_e32 v3, v129
	v_readlane_b32 s18, v253, 18
	v_lshl_add_u64 v[124:125], v[0:1], 0, v[2:3]
	v_readlane_b32 s19, v253, 19
	v_and_b32_e32 v2, 0x780, v9
	v_readlane_b32 s41, v254, 36
	v_readlane_b32 s42, v254, 37
	v_readlane_b32 s43, v254, 38
	v_readlane_b32 s44, v254, 39
	v_readlane_b32 s45, v254, 40
	v_readlane_b32 s46, v254, 41
	v_readlane_b32 s47, v254, 42
	v_readlane_b32 s50, v254, 45
	v_readlane_b32 s51, v254, 46
	v_readlane_b32 s52, v254, 47
	v_readlane_b32 s53, v254, 48
	v_readlane_b32 s54, v254, 49
	v_readlane_b32 s55, v254, 50
	v_lshl_add_u64 v[0:1], s[18:19], 0, v[4:5]
	v_add_u32_e32 v2, v2, v8
	v_lshlrev_b32_e32 v10, 6, v6
